# attention softmax: removed the redundant select around exp (masked scores are -1e30, exp underflows to exactly 0)
# baseline (speedup 1.0000x reference)
; __device__ __forceinline__ unsigned cvt_pk_bf16(float lo, float hi) { f32x2_t v = {lo, hi}; bf2_t r = __builtin_convertvector(v, bf2_t); return __builtin_bit_cast(unsigned, r); }
; __device__ __forceinline__ s16x4_t lds_tr_b64(const bf16_t* p) { return __builtin_amdgcn_ds_read_tr16_b64_v4i16((LAS s16x4_t*)p); }
; __device__ __forceinline__ void attn_item(const Ctx& C, int it, int itn, u32x4 (&kv)[4], u32x4 (&vv)[4], u32x4 (&qv)[2]) {
;     ...
;     float mx = -1e30f;
; #pragma unroll
;     for (int kt = 0; kt < 9; ++kt)
; #pragma unroll
;         for (int rg = 0; rg < 4; ++rg) { const int cidx = 16 * (w + kt) + 4 * quad + rg, rel = cidx - 64 - a, ik = 128 * jb - 64 + cidx;
;             const bool valid = (rel >= -64) && (rel <= 64) && (ik >= 0) && (ik < n);
;             const int bi = rel < -64 ? 0 : (rel > 64 ? 128 : rel + 64);
;             const float s = valid ? sc[kt][rg] * 0.125f + bt[bi] : -1e30f;
;             sc[kt][rg] = s; mx = fmaxf(mx, s); }
;     mx = fmaxf(mx, __shfl_xor(mx, 16)); mx = fmaxf(mx, __shfl_xor(mx, 32));
;     float lsum = 0.f;
; #pragma unroll
;     for (int kt = 0; kt < 9; ++kt)
; #pragma unroll
;         for (int rg = 0; rg < 4; ++rg) { const float s = sc[kt][rg]; const float p = (s > -1e29f) ? __expf(s - mx) : 0.f; sc[kt][rg] = p; lsum += p; }
;     lsum += __shfl_xor(lsum, 16); lsum += __shfl_xor(lsum, 32);
;     f32x4 oo[4];
; #pragma unroll
;     for (int dt = 0; dt < 4; ++dt) oo[dt] = (f32x4){0.f, 0.f, 0.f, 0.f};
; #pragma unroll
;     for (int pp = 0; pp < 5; ++pp) { const int ktA = 2 * pp, ktB = 2 * pp + 1, ktBc = ktB < 9 ? ktB : 8;
;         union { bf16x8 v; unsigned u[4]; } pf;
;         pf.u[0] = cvt_pk_bf16(sc[ktA][0], sc[ktA][1]); pf.u[1] = cvt_pk_bf16(sc[ktA][2], sc[ktA][3]);
;         if (ktB < 9) { pf.u[2] = cvt_pk_bf16(sc[ktBc][0], sc[ktBc][1]); pf.u[3] = cvt_pk_bf16(sc[ktBc][2], sc[ktBc][3]); } else { pf.u[2] = 0u; pf.u[3] = 0u; }
; #pragma unroll
;         for (int dt = 0; dt < 4; ++dt) { const bf16_t* vr = Vs + (16 * w + 4 * quad + (fr >> 2)) * 72 + 16 * dt + 4 * (fr & 3);
;             union { bf16x8 v; s16x4_t h[2]; } vf; vf.h[0] = lds_tr_b64(vr + 16 * ktA * 72); vf.h[1] = lds_tr_b64(vr + 16 * ktBc * 72);
;             oo[dt] = __builtin_amdgcn_mfma_f32_16x16x32_bf16(vf.v, pf.v, oo[dt], 0, 0, 0); } }
.LBB0_431:
	s_or_b64 exec, exec, s[0:1]
	s_mov_b32 s0, 0xf149f2ca
	v_max3_f32 v40, v195, s0, v91
	v_max3_f32 v40, v40, v194, v79
	v_max3_f32 v40, v40, v74, v64
	v_max3_f32 v40, v40, v75, v70
	v_max3_f32 v40, v40, v72, v71
	v_max3_f32 v40, v40, v73, v66
	v_max3_f32 v40, v40, v69, v67
	v_max3_f32 v40, v40, v68, v60
	v_max3_f32 v40, v40, v62, v61
	v_max3_f32 v40, v40, v63, v57
	v_max3_f32 v40, v40, v59, v56
	v_max3_f32 v40, v40, v58, v53
	v_max3_f32 v40, v40, v55, v52
	v_max3_f32 v40, v40, v54, v49
	v_max3_f32 v40, v40, v50, v48
	v_max3_f32 v40, v40, v45, v44
	v_max3_f32 v40, v40, v47, v46
	v_max3_f32 v40, v40, v51, v41
	ds_bpermute_b32 v42, v169, v40
	s_mov_b32 s1, 0xefa18f08
	s_sub_i32 s0, 5, s52
	s_lshr_b32 s0, s47, s0
	s_waitcnt lgkmcnt(0)
	v_max_f32_e32 v42, v42, v42
	v_max_f32_e32 v40, v40, v42
	ds_bpermute_b32 v42, v170, v40
	s_waitcnt lgkmcnt(0)
	v_max_f32_e32 v42, v42, v42
	v_max_f32_e32 v42, v40, v42
	v_sub_f32_e32 v40, v195, v42
	v_mul_f32_e32 v40, 0x3fb8aa3b, v40
	v_sub_f32_e32 v43, v91, v42
	v_exp_f32_e32 v40, v40
	v_mul_f32_e32 v43, 0x3fb8aa3b, v43
	v_exp_f32_e32 v43, v43
	v_add_f32_e32 v76, 0, v40
	s_nop 0
	v_add_f32_e32 v77, v43, v76
	v_sub_f32_e32 v76, v194, v42
	v_mul_f32_e32 v76, 0x3fb8aa3b, v76
	v_exp_f32_e32 v76, v76
	v_cvt_pk_bf16_f32 v196, v40, v43
	s_nop 0
	v_add_f32_e32 v91, v76, v77
	v_sub_f32_e32 v77, v79, v42
	v_mul_f32_e32 v77, 0x3fb8aa3b, v77
	v_exp_f32_e32 v77, v77
	s_nop 1
	v_sub_f32_e32 v74, v74, v42
	v_mul_f32_e32 v74, 0x3fb8aa3b, v74
	v_exp_f32_e32 v74, v74
	v_add_f32_e32 v79, v77, v91
	v_cvt_pk_bf16_f32 v197, v76, v77
	v_sub_f32_e32 v64, v64, v42
	v_mul_f32_e32 v64, 0x3fb8aa3b, v64
	v_exp_f32_e32 v64, v64
	v_add_f32_e32 v91, v74, v79
	v_mov_b32_e32 v79, v64
	v_sub_f32_e32 v75, v75, v42
	v_mul_f32_e32 v75, 0x3fb8aa3b, v75
	v_exp_f32_e32 v75, v75
	v_add_f32_e32 v64, v79, v91
	v_cvt_pk_bf16_f32 v198, v74, v79
	v_sub_f32_e32 v70, v70, v42
	v_mul_f32_e32 v70, 0x3fb8aa3b, v70
	v_exp_f32_e32 v70, v70
	v_add_f32_e32 v64, v75, v64
	v_mov_b32_e32 v91, v70
	v_add_f32_e32 v70, v91, v64
	v_sub_f32_e32 v64, v72, v42
	v_mul_f32_e32 v64, 0x3fb8aa3b, v64
	v_exp_f32_e32 v64, v64
	v_cvt_pk_bf16_f32 v199, v75, v91
	ds_read_b64_tr_b16 v[76:77], v171 offset:57600
	ds_read_b64_tr_b16 v[74:75], v171 offset:55296
	ds_read_b64_tr_b16 v[200:201], v171 offset:55328
	v_add_f32_e32 v72, v64, v70
	v_sub_f32_e32 v70, v71, v42
	v_mul_f32_e32 v70, 0x3fb8aa3b, v70
	v_sub_f32_e32 v71, v73, v42
	v_exp_f32_e32 v70, v70
	v_mul_f32_e32 v71, 0x3fb8aa3b, v71
	v_exp_f32_e32 v71, v71
	ds_read_b64_tr_b16 v[202:203], v171 offset:57632
	v_add_f32_e32 v72, v70, v72
	ds_read_b64_tr_b16 v[204:205], v171 offset:55360
	ds_read_b64_tr_b16 v[206:207], v171 offset:57664
	v_sub_f32_e32 v66, v66, v42
	v_mul_f32_e32 v66, 0x3fb8aa3b, v66
	v_exp_f32_e32 v66, v66
	v_add_f32_e32 v72, v71, v72
	ds_read_b64_tr_b16 v[208:209], v171 offset:55392
	ds_read_b64_tr_b16 v[210:211], v171 offset:57696
	s_waitcnt lgkmcnt(6)
	v_mfma_f32_16x16x32_bf16 v[74:77], v[74:77], v[196:199], 0
	v_sub_f32_e32 v69, v69, v42
	v_mul_f32_e32 v69, 0x3fb8aa3b, v69
	v_exp_f32_e32 v69, v69
	v_add_f32_e32 v72, v66, v72
	s_waitcnt lgkmcnt(4)
	v_mfma_f32_16x16x32_bf16 v[200:203], v[200:203], v[196:199], 0
	v_mov_b32_e32 v91, v65
	v_sub_f32_e32 v67, v67, v42
	v_mul_f32_e32 v67, 0x3fb8aa3b, v67
	v_exp_f32_e32 v67, v67
	v_add_f32_e32 v72, v69, v72
	s_waitcnt lgkmcnt(2)
	v_mfma_f32_16x16x32_bf16 v[204:207], v[204:207], v[196:199], 0
	v_sub_f32_e32 v68, v68, v42
	v_mul_f32_e32 v68, 0x3fb8aa3b, v68
	v_exp_f32_e32 v68, v68
	v_add_f32_e32 v72, v67, v72
	s_waitcnt lgkmcnt(0)
	v_mfma_f32_16x16x32_bf16 v[196:199], v[208:211], v[196:199], 0
	v_cvt_pk_bf16_f32 v209, v71, v66
	v_sub_f32_e32 v60, v60, v42
	v_mul_f32_e32 v60, 0x3fb8aa3b, v60
	v_exp_f32_e32 v60, v60
	v_add_f32_e32 v73, v68, v72
	v_cvt_pk_bf16_f32 v210, v69, v67
	v_cvt_pk_bf16_f32 v208, v64, v70
	v_mov_b32_e32 v72, v60
	v_sub_f32_e32 v60, v62, v42
	v_mul_f32_e32 v60, 0x3fb8aa3b, v60
	v_exp_f32_e32 v60, v60
	v_add_f32_e32 v73, v72, v73
	v_cvt_pk_bf16_f32 v211, v68, v72
	v_sub_f32_e32 v61, v61, v42
	v_mul_f32_e32 v61, 0x3fb8aa3b, v61
	v_exp_f32_e32 v61, v61
	v_add_f32_e32 v62, v60, v73
	ds_read_b64_tr_b16 v[66:67], v171 offset:59904
	ds_read_b64_tr_b16 v[68:69], v171 offset:62208
	s_waitcnt lgkmcnt(0)
	v_mfma_f32_16x16x32_bf16 v[66:69], v[66:69], v[208:211], v[74:77]
	v_add_f32_e32 v73, v61, v62
	v_sub_f32_e32 v62, v63, v42
	v_mul_f32_e32 v62, 0x3fb8aa3b, v62
	v_exp_f32_e32 v62, v62
	ds_read_b64_tr_b16 v[74:75], v171 offset:59936
	ds_read_b64_tr_b16 v[76:77], v171 offset:62240
	s_waitcnt lgkmcnt(0)
	v_mfma_f32_16x16x32_bf16 v[74:77], v[74:77], v[208:211], v[200:203]
	v_sub_f32_e32 v57, v57, v42
	v_mul_f32_e32 v57, 0x3fb8aa3b, v57
	v_exp_f32_e32 v57, v57
	v_add_f32_e32 v63, v62, v73
	ds_read_b64_tr_b16 v[200:201], v171 offset:59968
	ds_read_b64_tr_b16 v[202:203], v171 offset:62272
	s_waitcnt lgkmcnt(0)
	v_mfma_f32_16x16x32_bf16 v[200:203], v[200:203], v[208:211], v[204:207]
	v_sub_f32_e32 v59, v59, v42
	v_mul_f32_e32 v59, 0x3fb8aa3b, v59
	v_exp_f32_e32 v59, v59
	v_add_f32_e32 v63, v57, v63
	ds_read_b64_tr_b16 v[204:205], v171 offset:60000
	ds_read_b64_tr_b16 v[206:207], v171 offset:62304
	v_cvt_pk_bf16_f32 v60, v60, v61
	v_sub_f32_e32 v56, v56, v42
	v_mul_f32_e32 v56, 0x3fb8aa3b, v56
	v_exp_f32_e32 v56, v56
	v_add_f32_e32 v63, v59, v63
	v_cvt_pk_bf16_f32 v61, v62, v57
	s_waitcnt lgkmcnt(0)
; __device__ __forceinline__ unsigned cvt_pk_bf16(float lo, float hi) { f32x2_t v = {lo, hi}; bf2_t r = __builtin_convertvector(v, bf2_t); return __builtin_bit_cast(unsigned, r); }
; __device__ __forceinline__ s16x4_t lds_tr_b64(const bf16_t* p) { return __builtin_amdgcn_ds_read_tr16_b64_v4i16((LAS s16x4_t*)p); }
; __device__ __forceinline__ void attn_item(const Ctx& C, int it, int itn, u32x4 (&kv)[4], u32x4 (&vv)[4], u32x4 (&qv)[2]) {
;     ...
; #pragma unroll
;     for (int kt = 0; kt < 9; ++kt)
; #pragma unroll
;         for (int rg = 0; rg < 4; ++rg) { const float s = sc[kt][rg]; const float p = (s > -1e29f) ? __expf(s - mx) : 0.f; sc[kt][rg] = p; lsum += p; }
;     lsum += __shfl_xor(lsum, 16); lsum += __shfl_xor(lsum, 32);
;     f32x4 oo[4];
; #pragma unroll
;     for (int dt = 0; dt < 4; ++dt) oo[dt] = (f32x4){0.f, 0.f, 0.f, 0.f};
; #pragma unroll
;     for (int pp = 0; pp < 5; ++pp) { const int ktA = 2 * pp, ktB = 2 * pp + 1, ktBc = ktB < 9 ? ktB : 8;
;         union { bf16x8 v; unsigned u[4]; } pf;
;         pf.u[0] = cvt_pk_bf16(sc[ktA][0], sc[ktA][1]); pf.u[1] = cvt_pk_bf16(sc[ktA][2], sc[ktA][3]);
;         if (ktB < 9) { pf.u[2] = cvt_pk_bf16(sc[ktBc][0], sc[ktBc][1]); pf.u[3] = cvt_pk_bf16(sc[ktBc][2], sc[ktBc][3]); } else { pf.u[2] = 0u; pf.u[3] = 0u; }
; #pragma unroll
;         for (int dt = 0; dt < 4; ++dt) { const bf16_t* vr = Vs + (16 * w + 4 * quad + (fr >> 2)) * 72 + 16 * dt + 4 * (fr & 3);
;             union { bf16x8 v; s16x4_t h[2]; } vf; vf.h[0] = lds_tr_b64(vr + 16 * ktA * 72); vf.h[1] = lds_tr_b64(vr + 16 * ktBc * 72);
;             oo[dt] = __builtin_amdgcn_mfma_f32_16x16x32_bf16(vf.v, pf.v, oo[dt], 0, 0, 0); } }
;     const float inv = 1.0f / lsum;
	v_mfma_f32_16x16x32_bf16 v[196:199], v[204:207], v[208:211], v[196:199]
	v_sub_f32_e32 v58, v58, v42
	v_mul_f32_e32 v58, 0x3fb8aa3b, v58
	v_exp_f32_e32 v58, v58
	v_add_f32_e32 v63, v56, v63
	v_cvt_pk_bf16_f32 v62, v59, v56
	v_mov_b32_e32 v64, v65
	v_sub_f32_e32 v53, v53, v42
	v_mul_f32_e32 v53, 0x3fb8aa3b, v53
	v_exp_f32_e32 v53, v53
	v_add_f32_e32 v73, v58, v63
	v_mov_b32_e32 v63, v53
	v_sub_f32_e32 v53, v55, v42
	v_mul_f32_e32 v53, 0x3fb8aa3b, v53
	v_exp_f32_e32 v53, v53
	v_add_f32_e32 v73, v63, v73
	v_cvt_pk_bf16_f32 v63, v58, v63
	v_sub_f32_e32 v52, v52, v42
	v_mul_f32_e32 v52, 0x3fb8aa3b, v52
	v_exp_f32_e32 v52, v52
	ds_read_b64_tr_b16 v[56:57], v171 offset:64512
	ds_read_b64_tr_b16 v[58:59], v172 offset:11520
	ds_read_b64_tr_b16 v[70:71], v172 offset:11552
	v_add_f32_e32 v55, v53, v73
	s_waitcnt lgkmcnt(1)
	v_mfma_f32_16x16x32_bf16 v[56:59], v[56:59], v[60:63], v[66:69]
	v_sub_f32_e32 v54, v54, v42
	v_mul_f32_e32 v54, 0x3fb8aa3b, v54
	v_exp_f32_e32 v54, v54
	v_add_f32_e32 v55, v52, v55
	ds_read_b64_tr_b16 v[68:69], v171 offset:64544
	s_waitcnt lgkmcnt(0)
	v_mfma_f32_16x16x32_bf16 v[66:69], v[68:71], v[60:63], v[74:77]
	v_sub_f32_e32 v49, v49, v42
	v_mul_f32_e32 v49, 0x3fb8aa3b, v49
	v_exp_f32_e32 v49, v49
	v_add_f32_e32 v55, v54, v55
	ds_read_b64_tr_b16 v[74:75], v171 offset:64576
	ds_read_b64_tr_b16 v[76:77], v172 offset:11584
	s_waitcnt lgkmcnt(0)
	v_mfma_f32_16x16x32_bf16 v[74:77], v[74:77], v[60:63], v[200:203]
	v_sub_f32_e32 v50, v50, v42
	v_mul_f32_e32 v50, 0x3fb8aa3b, v50
	v_exp_f32_e32 v50, v50
	v_add_f32_e32 v55, v49, v55
	ds_read_b64_tr_b16 v[200:201], v171 offset:64608
	ds_read_b64_tr_b16 v[202:203], v172 offset:11616
	v_cvt_pk_bf16_f32 v52, v53, v52
	v_sub_f32_e32 v48, v48, v42
	v_mul_f32_e32 v48, 0x3fb8aa3b, v48
	v_exp_f32_e32 v48, v48
	v_add_f32_e32 v73, v50, v55
	v_cvt_pk_bf16_f32 v53, v54, v49
	s_waitcnt lgkmcnt(0)
	v_mfma_f32_16x16x32_bf16 v[60:63], v[200:203], v[60:63], v[196:199]
	v_mov_b32_e32 v55, v48
	v_sub_f32_e32 v45, v45, v42
	v_mul_f32_e32 v45, 0x3fb8aa3b, v45
	v_exp_f32_e32 v45, v45
	v_add_f32_e32 v48, v55, v73
	v_cvt_pk_bf16_f32 v54, v50, v55
	v_mov_b32_e32 v73, v45
	v_sub_f32_e32 v44, v44, v42
	v_mul_f32_e32 v44, 0x3fb8aa3b, v44
	v_exp_f32_e32 v44, v44
	v_add_f32_e32 v45, v73, v48
	v_mov_b32_e32 v194, v44
	v_add_f32_e32 v44, v194, v45
	v_sub_f32_e32 v45, v47, v42
	v_cvt_pk_bf16_f32 v55, v73, v194
	ds_read_b64_tr_b16 v[70:71], v172 offset:13824
	ds_read_b64_tr_b16 v[72:73], v172 offset:16128
	v_mul_f32_e32 v45, 0x3fb8aa3b, v45
	v_exp_f32_e32 v45, v45
	s_waitcnt lgkmcnt(0)
	v_mfma_f32_16x16x32_bf16 v[56:59], v[70:73], v[52:55], v[56:59]
	ds_read_b64_tr_b16 v[70:71], v172 offset:13856
	ds_read_b64_tr_b16 v[72:73], v172 offset:16160
	v_sub_f32_e32 v46, v46, v42
	v_mul_f32_e32 v46, 0x3fb8aa3b, v46
	v_sub_f32_e32 v47, v51, v42
	v_exp_f32_e32 v46, v46
	v_mul_f32_e32 v47, 0x3fb8aa3b, v47
	v_exp_f32_e32 v47, v47
	s_waitcnt lgkmcnt(0)
	v_mfma_f32_16x16x32_bf16 v[66:69], v[70:73], v[52:55], v[66:69]
	ds_read_b64_tr_b16 v[70:71], v172 offset:13888
	ds_read_b64_tr_b16 v[72:73], v172 offset:16192
	s_waitcnt lgkmcnt(0)
	v_mfma_f32_16x16x32_bf16 v[70:73], v[70:73], v[52:55], v[74:77]
	v_sub_f32_e32 v41, v41, v42
	v_mul_f32_e32 v41, 0x3fb8aa3b, v41
	v_exp_f32_e32 v41, v41
	ds_read_b64_tr_b16 v[74:75], v172 offset:13920
	ds_read_b64_tr_b16 v[76:77], v172 offset:16224
	v_add_f32_e32 v44, v45, v44
	v_add_f32_e32 v44, v46, v44
	v_mov_b32_e32 v48, v41
	v_add_f32_e32 v44, v47, v44
	s_waitcnt lgkmcnt(0)
	v_mfma_f32_16x16x32_bf16 v[50:53], v[74:77], v[52:55], v[60:63]
	v_add_f32_e32 v41, v48, v44
	ds_bpermute_b32 v44, v169, v41
	ds_read_b64_tr_b16 v[54:55], v172 offset:18464
	v_cvt_pk_bf16_f32 v62, v45, v46
	v_cvt_pk_bf16_f32 v63, v47, v48
	ds_read_b64_tr_b16 v[46:47], v172 offset:18432
	s_waitcnt lgkmcnt(2)
	v_add_f32_e32 v41, v41, v44
	ds_bpermute_b32 v44, v170, v41
	s_lshl_b32 s1, s51, 12
	s_or_b32 s0, s0, s1
	s_waitcnt lgkmcnt(1)
	v_mov_b32_e32 v48, v46
	v_mov_b32_e32 v49, v47
	s_waitcnt lgkmcnt(0)
	v_add_f32_e32 v41, v41, v44
	v_div_scale_f32 v40, s[48:49], v41, v41, 1.0
	v_mfma_f32_16x16x32_bf16 v[46:49], v[46:49], v[62:65], v[56:59]
	v_rcp_f32_e32 v43, v40
	s_nop 1
	v_mov_b32_e32 v56, v54
	v_mov_b32_e32 v57, v55
	ds_read_b64_tr_b16 v[58:59], v172 offset:18496
	v_fma_f32 v44, -v40, v43, 1.0
	v_mfma_f32_16x16x32_bf16 v[54:57], v[54:57], v[62:65], v[66:69]
	v_fmac_f32_e32 v43, v44, v43
	s_nop 1
	ds_read_b64_tr_b16 v[66:67], v172 offset:18528
	s_waitcnt lgkmcnt(1)
	v_mov_b32_e32 v60, v58
	v_mov_b32_e32 v61, v59
	v_div_scale_f32 v44, vcc, 1.0, v41, 1.0
	s_waitcnt lgkmcnt(0)
	v_mov_b32_e32 v68, v66
	v_mov_b32_e32 v69, v67
	v_mul_f32_e32 v45, v44, v43
	v_mfma_f32_16x16x32_bf16 v[58:61], v[58:61], v[62:65], v[70:73]
	s_barrier
; __device__ __forceinline__ unsigned cvt_pk_bf16(float lo, float hi) { f32x2_t v = {lo, hi}; bf2_t r = __builtin_convertvector(v, bf2_t); return __builtin_bit_cast(unsigned, r); }
;     __device__ __forceinline__ float* fp(size_t off) const { return (float*)(ws + off); }
; __device__ __forceinline__ void attn_item(const Ctx& C, int it, int itn, u32x4 (&kv)[4], u32x4 (&vv)[4], u32x4 (&qv)[2]) {
;     ...
;     const float inv = 1.0f / lsum;
;     const size_t tok = (size_t)(b * SEQ + r + dil * (128 * jb + a));
;     __syncthreads();
; #pragma unroll
;     for (int dt = 0; dt < 4; ++dt) { u32x2 o; o.x = cvt_pk_bf16(oo[dt][0] * inv, oo[dt][1] * inv); o.y = cvt_pk_bf16(oo[dt][2] * inv, oo[dt][3] * inv);
;         *(u32x2*)(pd + tok * 2304 + hq * 64 + 16 * dt + 4 * quad) = o; }
;     if (quad == 0) C.fp(OFF_LSE)[((size_t)g * M_TOK + tok) * 4 + (hq & 3)] = mx + __logf(lsum);
	v_mfma_f32_16x16x32_bf16 v[50:53], v[66:69], v[62:65], v[50:53]
	v_fma_f32 v62, -v40, v45, v44
	v_fmac_f32_e32 v45, v62, v43
	v_fma_f32 v40, -v40, v45, v44
	v_div_fmas_f32 v40, v40, v43, v45
	v_div_fixup_f32 v44, v40, v41, 1.0
	v_add_u32_e32 v40, s46, v83
	v_lshlrev_b32_e32 v40, s52, v40
	v_add_u32_e32 v40, s0, v40
	v_mov_b64_e32 v[62:63], s[42:43]
	v_mad_i64_i32 v[62:63], s[0:1], v40, s66, v[62:63]
	s_lshl_b32 s0, s41, 6
	s_ashr_i32 s1, s0, 31
	v_lshl_add_u64 v[62:63], s[0:1], 1, v[62:63]
	v_pk_mul_f32 v[46:47], v[44:45], v[46:47] op_sel_hi:[0,1]
	v_pk_mul_f32 v[48:49], v[44:45], v[48:49] op_sel_hi:[0,1]
	v_lshl_add_u64 v[62:63], v[62:63], 0, v[90:91]
	v_cvt_pk_bf16_f32 v46, v46, v47
	v_cvt_pk_bf16_f32 v47, v48, v49
	global_store_dwordx2 v[62:63], v[46:47], off
	v_pk_mul_f32 v[46:47], v[44:45], v[54:55] op_sel_hi:[0,1]
	v_pk_mul_f32 v[48:49], v[44:45], v[56:57] op_sel_hi:[0,1]
	v_cvt_pk_bf16_f32 v46, v46, v47
	v_cvt_pk_bf16_f32 v47, v48, v49
	global_store_dwordx2 v[62:63], v[46:47], off offset:32
	v_pk_mul_f32 v[46:47], v[44:45], v[58:59] op_sel_hi:[0,1]
	v_pk_mul_f32 v[48:49], v[44:45], v[60:61] op_sel_hi:[0,1]
	v_cvt_pk_bf16_f32 v46, v46, v47
	v_cvt_pk_bf16_f32 v47, v48, v49
	global_store_dwordx2 v[62:63], v[46:47], off offset:64
	v_pk_mul_f32 v[46:47], v[44:45], v[50:51] op_sel_hi:[0,1]
	v_pk_mul_f32 v[44:45], v[44:45], v[52:53] op_sel_hi:[0,1]
	v_cvt_pk_bf16_f32 v46, v46, v47
	v_cvt_pk_bf16_f32 v47, v44, v45
	global_store_dwordx2 v[62:63], v[46:47], off offset:96
	s_and_saveexec_b64 s[0:1], s[20:21]
	s_cbranch_execz .LBB0_344
	v_cmp_gt_f32_e32 vcc, s54, v41
	s_ashr_i32 s41, s40, 31
	s_lshl_b64 s[40:41], s[40:41], 19
	v_cndmask_b32_e64 v43, 0, 32, vcc
	v_ldexp_f32 v41, v41, v43
	v_log_f32_e32 v43, v41
	v_readlane_b32 s46, v255, 43
	v_cndmask_b32_e32 v44, 0, v225, vcc
	s_add_u32 s40, s46, s40
	v_mul_f32_e32 v45, 0x3f317217, v43
	v_fma_f32 v45, v43, s56, -v45
	v_fmac_f32_e32 v45, 0x3377d1cf, v43
	v_fmac_f32_e32 v45, 0x3f317217, v43
	v_cmp_lt_f32_e64 vcc, |v43|, s57
	v_readlane_b32 s46, v255, 44
	v_ashrrev_i32_e32 v41, 31, v40
	v_cndmask_b32_e32 v43, v43, v45, vcc
	s_addc_u32 s41, s46, s41
	s_lshr_b32 s36, s36, 3
	v_sub_f32_e32 v43, v43, v44
	v_lshl_add_u64 v[40:41], v[40:41], 4, s[40:41]
	s_and_b32 s36, s36, 12
	v_add_f32_e32 v42, v42, v43
	v_lshl_add_u64 v[40:41], v[40:41], 0, s[36:37]
	global_store_dword v[40:41], v42, off
	s_branch .LBB0_344
